# weight transpose staging loops: 32 row loads in flight per item (P0 w_in, P2 tail w_out, P6 tail w_up w_down)
# speedup vs baseline: 1.0197x; 1.0150x over previous
; template <int MAPID> __device__ __forceinline__ void transpose_item(const float* __restrict__ W, int K, int Nsrc, bf16_t* __restrict__ WT, int nblk, float* scr, int item, int lane) {
;     const int kb = item / nblk, nb = item % nblk, k0 = 64 * kb, n0 = 32 * nb;
;     const int srcc = colmap<MAPID>(n0 + (lane & 31));
; #pragma unroll 8
;     for (int i = 0; i < 32; ++i) { const int kk = 2 * i + (lane >> 5); scr[kk * 33 + (lane & 31)] = srcc >= 0 ? __builtin_nontemporal_load(W + (size_t)(k0 + kk) * Nsrc + srcc) : 0.f; }
;     asm volatile("s_waitcnt lgkmcnt(0)" ::: "memory");
; __device__ __forceinline__ void phase0(const Args& a, unsigned char* lds, int tid, int lane, int wave) {
;     ...
;         constexpr int I_IN = 32 * (NP / 32);
;         for (int it = gw; it < I_IN; it += NGW) transpose_item<1>(a.in[13], DM, WIN_N, (bf16_t*)(ws + WS_WIN), NP / 32, scr, it, lane);
.LBB0_70:
	s_or_b64 exec, exec, s[4:5]
	s_lshl_b32 s4, s8, 6
	v_cmp_lt_i32_e32 vcc, -1, v0
	v_lshlrev_b64 v[18:19], 2, v[0:1]
	v_or_b32_e32 v0, s4, v29
	v_mad_i64_i32 v[6:7], s[6:7], v0, s13, v[18:19]
	v_or_b32_e32 v0, s4, v30
	v_mad_i64_i32 v[8:9], s[6:7], v0, s13, v[18:19]
	v_or_b32_e32 v0, s4, v31
	v_mad_i64_i32 v[10:11], s[6:7], v0, s13, v[18:19]
	v_or_b32_e32 v0, s4, v32
	v_mad_i64_i32 v[12:13], s[6:7], v0, s13, v[18:19]
	v_or_b32_e32 v0, s4, v33
	v_mad_i64_i32 v[14:15], s[6:7], v0, s13, v[18:19]
	v_or_b32_e32 v0, s4, v34
	v_or_b32_e32 v4, s4, v28
	v_mad_i64_i32 v[16:17], s[6:7], v0, s13, v[18:19]
	v_or_b32_e32 v0, s4, v21
	v_mad_i64_i32 v[4:5], s[6:7], v4, s13, v[18:19]
	v_mad_i64_i32 v[18:19], s[6:7], v0, s13, v[18:19]
	v_lshl_add_u64 v[4:5], s[86:87], 0, v[4:5]
	v_lshl_add_u64 v[6:7], s[86:87], 0, v[6:7]
	v_lshl_add_u64 v[8:9], s[86:87], 0, v[8:9]
	v_lshl_add_u64 v[10:11], s[86:87], 0, v[10:11]
	v_lshl_add_u64 v[12:13], s[86:87], 0, v[12:13]
	v_lshl_add_u64 v[14:15], s[86:87], 0, v[14:15]
	v_lshl_add_u64 v[16:17], s[86:87], 0, v[16:17]
	v_lshl_add_u64 v[18:19], s[86:87], 0, v[18:19]
	s_mov_b64 s[6:7], 0
	v_mov_b32_e32 v0, v27
	v_mov_b32_e32 v44, 0
	v_mov_b32_e32 v45, 0
	v_mov_b32_e32 v46, 0
	v_mov_b32_e32 v47, 0
	v_mov_b32_e32 v48, 0
	v_mov_b32_e32 v49, 0
	v_mov_b32_e32 v50, 0
	v_mov_b32_e32 v51, 0
	v_mov_b32_e32 v52, 0
	v_mov_b32_e32 v53, 0
	v_mov_b32_e32 v54, 0
	v_mov_b32_e32 v55, 0
	v_mov_b32_e32 v56, 0
	v_mov_b32_e32 v57, 0
	v_mov_b32_e32 v58, 0
	v_mov_b32_e32 v59, 0
	v_mov_b32_e32 v60, 0
	v_mov_b32_e32 v61, 0
	v_mov_b32_e32 v62, 0
	v_mov_b32_e32 v63, 0
	v_mov_b32_e32 v64, 0
	v_mov_b32_e32 v65, 0
	v_mov_b32_e32 v66, 0
	v_mov_b32_e32 v67, 0
	v_mov_b32_e32 v68, 0
	v_mov_b32_e32 v69, 0
	v_mov_b32_e32 v70, 0
	v_mov_b32_e32 v71, 0
	v_mov_b32_e32 v72, 0
	v_mov_b32_e32 v73, 0
	v_mov_b32_e32 v74, 0
	v_mov_b32_e32 v75, 0
	s_and_saveexec_b64 s[8:9], vcc
	v_lshl_add_u64 v[36:37], v[18:19], 0, s[6:7]
	global_load_dword v44, v[36:37], off nt
	v_lshl_add_u64 v[36:37], v[16:17], 0, s[6:7]
	global_load_dword v45, v[36:37], off nt
	v_lshl_add_u64 v[36:37], v[14:15], 0, s[6:7]
	global_load_dword v46, v[36:37], off nt
	v_lshl_add_u64 v[36:37], v[12:13], 0, s[6:7]
	global_load_dword v47, v[36:37], off nt
	v_lshl_add_u64 v[36:37], v[10:11], 0, s[6:7]
	global_load_dword v48, v[36:37], off nt
	v_lshl_add_u64 v[36:37], v[8:9], 0, s[6:7]
	global_load_dword v49, v[36:37], off nt
	v_lshl_add_u64 v[36:37], v[6:7], 0, s[6:7]
	global_load_dword v50, v[36:37], off nt
	v_lshl_add_u64 v[36:37], v[4:5], 0, s[6:7]
	global_load_dword v51, v[36:37], off nt
	s_add_u32 s6, s6, 0x71800
	s_addc_u32 s7, s7, 0
	v_lshl_add_u64 v[36:37], v[18:19], 0, s[6:7]
	global_load_dword v52, v[36:37], off nt
	v_lshl_add_u64 v[36:37], v[16:17], 0, s[6:7]
	global_load_dword v53, v[36:37], off nt
	v_lshl_add_u64 v[36:37], v[14:15], 0, s[6:7]
	global_load_dword v54, v[36:37], off nt
	v_lshl_add_u64 v[36:37], v[12:13], 0, s[6:7]
	global_load_dword v55, v[36:37], off nt
	v_lshl_add_u64 v[36:37], v[10:11], 0, s[6:7]
	global_load_dword v56, v[36:37], off nt
	v_lshl_add_u64 v[36:37], v[8:9], 0, s[6:7]
	global_load_dword v57, v[36:37], off nt
	v_lshl_add_u64 v[36:37], v[6:7], 0, s[6:7]
	global_load_dword v58, v[36:37], off nt
	v_lshl_add_u64 v[36:37], v[4:5], 0, s[6:7]
	global_load_dword v59, v[36:37], off nt
	s_add_u32 s6, s6, 0x71800
	s_addc_u32 s7, s7, 0
	v_lshl_add_u64 v[36:37], v[18:19], 0, s[6:7]
	global_load_dword v60, v[36:37], off nt
	v_lshl_add_u64 v[36:37], v[16:17], 0, s[6:7]
	global_load_dword v61, v[36:37], off nt
	v_lshl_add_u64 v[36:37], v[14:15], 0, s[6:7]
	global_load_dword v62, v[36:37], off nt
	v_lshl_add_u64 v[36:37], v[12:13], 0, s[6:7]
	global_load_dword v63, v[36:37], off nt
	v_lshl_add_u64 v[36:37], v[10:11], 0, s[6:7]
	global_load_dword v64, v[36:37], off nt
	v_lshl_add_u64 v[36:37], v[8:9], 0, s[6:7]
	global_load_dword v65, v[36:37], off nt
	v_lshl_add_u64 v[36:37], v[6:7], 0, s[6:7]
	global_load_dword v66, v[36:37], off nt
	v_lshl_add_u64 v[36:37], v[4:5], 0, s[6:7]
	global_load_dword v67, v[36:37], off nt
	s_add_u32 s6, s6, 0x71800
	s_addc_u32 s7, s7, 0
	v_lshl_add_u64 v[36:37], v[18:19], 0, s[6:7]
	global_load_dword v68, v[36:37], off nt
	v_lshl_add_u64 v[36:37], v[16:17], 0, s[6:7]
	global_load_dword v69, v[36:37], off nt
	v_lshl_add_u64 v[36:37], v[14:15], 0, s[6:7]
	global_load_dword v70, v[36:37], off nt
	v_lshl_add_u64 v[36:37], v[12:13], 0, s[6:7]
	global_load_dword v71, v[36:37], off nt
	v_lshl_add_u64 v[36:37], v[10:11], 0, s[6:7]
	global_load_dword v72, v[36:37], off nt
	v_lshl_add_u64 v[36:37], v[8:9], 0, s[6:7]
	global_load_dword v73, v[36:37], off nt
	v_lshl_add_u64 v[36:37], v[6:7], 0, s[6:7]
	global_load_dword v74, v[36:37], off nt
	v_lshl_add_u64 v[36:37], v[4:5], 0, s[6:7]
	global_load_dword v75, v[36:37], off nt
	s_add_u32 s6, s6, 0x71800
	s_addc_u32 s7, s7, 0
	s_or_b64 exec, exec, s[8:9]
	s_waitcnt vmcnt(31)
	ds_write_b32 v0, v44
	s_waitcnt vmcnt(30)
	ds_write_b32 v0, v45 offset:264
	s_waitcnt vmcnt(29)
	ds_write_b32 v0, v46 offset:528
	s_waitcnt vmcnt(28)
	ds_write_b32 v0, v47 offset:792
	s_waitcnt vmcnt(27)
	ds_write_b32 v0, v48 offset:1056
	s_waitcnt vmcnt(26)
	ds_write_b32 v0, v49 offset:1320
	s_waitcnt vmcnt(25)
	ds_write_b32 v0, v50 offset:1584
	s_waitcnt vmcnt(24)
	ds_write_b32 v0, v51 offset:1848
	s_waitcnt vmcnt(23)
	ds_write_b32 v0, v52 offset:2112
	s_waitcnt vmcnt(22)
	ds_write_b32 v0, v53 offset:2376
	s_waitcnt vmcnt(21)
	ds_write_b32 v0, v54 offset:2640
	s_waitcnt vmcnt(20)
	ds_write_b32 v0, v55 offset:2904
	s_waitcnt vmcnt(19)
	ds_write_b32 v0, v56 offset:3168
	s_waitcnt vmcnt(18)
	ds_write_b32 v0, v57 offset:3432
	s_waitcnt vmcnt(17)
	ds_write_b32 v0, v58 offset:3696
	s_waitcnt vmcnt(16)
	ds_write_b32 v0, v59 offset:3960
	s_waitcnt vmcnt(15)
	ds_write_b32 v0, v60 offset:4224
	s_waitcnt vmcnt(14)
	ds_write_b32 v0, v61 offset:4488
	s_waitcnt vmcnt(13)
	ds_write_b32 v0, v62 offset:4752
	s_waitcnt vmcnt(12)
	ds_write_b32 v0, v63 offset:5016
	s_waitcnt vmcnt(11)
	ds_write_b32 v0, v64 offset:5280
	s_waitcnt vmcnt(10)
	ds_write_b32 v0, v65 offset:5544
	s_waitcnt vmcnt(9)
	ds_write_b32 v0, v66 offset:5808
	s_waitcnt vmcnt(8)
	ds_write_b32 v0, v67 offset:6072
	s_waitcnt vmcnt(7)
	ds_write_b32 v0, v68 offset:6336
	s_waitcnt vmcnt(6)
	ds_write_b32 v0, v69 offset:6600
	s_waitcnt vmcnt(5)
	ds_write_b32 v0, v70 offset:6864
	s_waitcnt vmcnt(4)
	ds_write_b32 v0, v71 offset:7128
	s_waitcnt vmcnt(3)
	ds_write_b32 v0, v72 offset:7392
	s_waitcnt vmcnt(2)
	ds_write_b32 v0, v73 offset:7656
	s_waitcnt vmcnt(1)
	ds_write_b32 v0, v74 offset:7920
	s_waitcnt vmcnt(0)
	ds_write_b32 v0, v75 offset:8184
	s_branch .LBB0_31

; template <int MAPID> __device__ __forceinline__ void transpose_item(const float* __restrict__ W, int K, int Nsrc, bf16_t* __restrict__ WT, int nblk, float* scr, int item, int lane) {
;     const int kb = item / nblk, nb = item % nblk, k0 = 64 * kb, n0 = 32 * nb;
;     const int srcc = colmap<MAPID>(n0 + (lane & 31));
; #pragma unroll 8
;     for (int i = 0; i < 32; ++i) { const int kk = 2 * i + (lane >> 5); scr[kk * 33 + (lane & 31)] = srcc >= 0 ? __builtin_nontemporal_load(W + (size_t)(k0 + kk) * Nsrc + srcc) : 0.f; }
; __device__ __forceinline__ void tail_wout(const Args& a, unsigned char* lds, int rank, int count, int lane, int wave) {
;     float* scr = (float*)(lds + wave * 8448);
;     for (int it = rank * 8 + wave; it < 32 * 64; it += count * 8) transpose_item<0>(a.in[19], DM, DM, (bf16_t*)(a.ws + WS_WOUT), 64, scr, it, lane);
; }
.LBB0_239:
	s_ashr_i32 s0, s5, 31
	s_lshr_b32 s0, s0, 26
	s_add_i32 s0, s5, s0
	s_and_b32 s2, s0, 0xffffffc0
	s_sub_i32 s0, s5, s2
	s_lshl_b32 s7, s0, 5
	s_cmp_gt_i32 s0, -1
	s_cselect_b64 s[0:1], -1, 0
	v_or_b32_e32 v0, s7, v6
	v_cndmask_b32_e64 v14, 0, 1, s[0:1]
	s_waitcnt lgkmcnt(0)
	v_lshl_add_u64 v[4:5], v[0:1], 2, s[82:83]
	v_or_b32_e32 v0, s2, v7
	v_cmp_ne_u32_e64 s[0:1], 1, v14
	v_mov_b32_e32 v14, v13
	s_mov_b32 s3, 0
	v_mov_b32_e32 v16, v0
	v_mov_b32_e32 v17, 0
	v_lshlrev_b64 v[16:17], 13, v[16:17]
	v_lshl_add_u64 v[36:37], v[4:5], 0, v[16:17]
	s_mov_b64 s[98:99], 0
	v_mov_b32_e32 v44, 0
	v_mov_b32_e32 v45, 0
	v_mov_b32_e32 v46, 0
	v_mov_b32_e32 v47, 0
	v_mov_b32_e32 v48, 0
	v_mov_b32_e32 v49, 0
	v_mov_b32_e32 v50, 0
	v_mov_b32_e32 v51, 0
	v_mov_b32_e32 v52, 0
	v_mov_b32_e32 v53, 0
	v_mov_b32_e32 v54, 0
	v_mov_b32_e32 v55, 0
	v_mov_b32_e32 v56, 0
	v_mov_b32_e32 v57, 0
	v_mov_b32_e32 v58, 0
	v_mov_b32_e32 v59, 0
	v_mov_b32_e32 v60, 0
	v_mov_b32_e32 v61, 0
	v_mov_b32_e32 v62, 0
	v_mov_b32_e32 v63, 0
	v_mov_b32_e32 v64, 0
	v_mov_b32_e32 v65, 0
	v_mov_b32_e32 v66, 0
	v_mov_b32_e32 v67, 0
	v_mov_b32_e32 v68, 0
	v_mov_b32_e32 v69, 0
	v_mov_b32_e32 v70, 0
	v_mov_b32_e32 v71, 0
	v_mov_b32_e32 v72, 0
	v_mov_b32_e32 v73, 0
	v_mov_b32_e32 v74, 0
	v_mov_b32_e32 v75, 0
	s_and_b64 vcc, exec, s[0:1]
	s_cbranch_vccnz .Ltr_b_skip
	v_lshl_add_u64 v[38:39], v[36:37], 0, s[98:99]
	global_load_dword v44, v[38:39], off nt
	s_add_u32 s98, s98, 0x4000
	s_addc_u32 s99, s99, 0
	v_lshl_add_u64 v[38:39], v[36:37], 0, s[98:99]
	global_load_dword v45, v[38:39], off nt
	s_add_u32 s98, s98, 0x4000
	s_addc_u32 s99, s99, 0
	v_lshl_add_u64 v[38:39], v[36:37], 0, s[98:99]
	global_load_dword v46, v[38:39], off nt
	s_add_u32 s98, s98, 0x4000
	s_addc_u32 s99, s99, 0
	v_lshl_add_u64 v[38:39], v[36:37], 0, s[98:99]
	global_load_dword v47, v[38:39], off nt
	s_add_u32 s98, s98, 0x4000
	s_addc_u32 s99, s99, 0
	v_lshl_add_u64 v[38:39], v[36:37], 0, s[98:99]
	global_load_dword v48, v[38:39], off nt
	s_add_u32 s98, s98, 0x4000
	s_addc_u32 s99, s99, 0
	v_lshl_add_u64 v[38:39], v[36:37], 0, s[98:99]
	global_load_dword v49, v[38:39], off nt
	s_add_u32 s98, s98, 0x4000
	s_addc_u32 s99, s99, 0
	v_lshl_add_u64 v[38:39], v[36:37], 0, s[98:99]
	global_load_dword v50, v[38:39], off nt
	s_add_u32 s98, s98, 0x4000
	s_addc_u32 s99, s99, 0
	v_lshl_add_u64 v[38:39], v[36:37], 0, s[98:99]
	global_load_dword v51, v[38:39], off nt
	s_add_u32 s98, s98, 0x4000
	s_addc_u32 s99, s99, 0
	v_lshl_add_u64 v[38:39], v[36:37], 0, s[98:99]
	global_load_dword v52, v[38:39], off nt
	s_add_u32 s98, s98, 0x4000
	s_addc_u32 s99, s99, 0
	v_lshl_add_u64 v[38:39], v[36:37], 0, s[98:99]
	global_load_dword v53, v[38:39], off nt
	s_add_u32 s98, s98, 0x4000
	s_addc_u32 s99, s99, 0
	v_lshl_add_u64 v[38:39], v[36:37], 0, s[98:99]
	global_load_dword v54, v[38:39], off nt
	s_add_u32 s98, s98, 0x4000
	s_addc_u32 s99, s99, 0
	v_lshl_add_u64 v[38:39], v[36:37], 0, s[98:99]
	global_load_dword v55, v[38:39], off nt
	s_add_u32 s98, s98, 0x4000
	s_addc_u32 s99, s99, 0
	v_lshl_add_u64 v[38:39], v[36:37], 0, s[98:99]
	global_load_dword v56, v[38:39], off nt
	s_add_u32 s98, s98, 0x4000
	s_addc_u32 s99, s99, 0
	v_lshl_add_u64 v[38:39], v[36:37], 0, s[98:99]
	global_load_dword v57, v[38:39], off nt
	s_add_u32 s98, s98, 0x4000
	s_addc_u32 s99, s99, 0
	v_lshl_add_u64 v[38:39], v[36:37], 0, s[98:99]
	global_load_dword v58, v[38:39], off nt
	s_add_u32 s98, s98, 0x4000
	s_addc_u32 s99, s99, 0
	v_lshl_add_u64 v[38:39], v[36:37], 0, s[98:99]
	global_load_dword v59, v[38:39], off nt
	s_add_u32 s98, s98, 0x4000
	s_addc_u32 s99, s99, 0
	v_lshl_add_u64 v[38:39], v[36:37], 0, s[98:99]
	global_load_dword v60, v[38:39], off nt
	s_add_u32 s98, s98, 0x4000
	s_addc_u32 s99, s99, 0
	v_lshl_add_u64 v[38:39], v[36:37], 0, s[98:99]
	global_load_dword v61, v[38:39], off nt
	s_add_u32 s98, s98, 0x4000
	s_addc_u32 s99, s99, 0
	v_lshl_add_u64 v[38:39], v[36:37], 0, s[98:99]
	global_load_dword v62, v[38:39], off nt
	s_add_u32 s98, s98, 0x4000
	s_addc_u32 s99, s99, 0
	v_lshl_add_u64 v[38:39], v[36:37], 0, s[98:99]
	global_load_dword v63, v[38:39], off nt
	s_add_u32 s98, s98, 0x4000
	s_addc_u32 s99, s99, 0
	v_lshl_add_u64 v[38:39], v[36:37], 0, s[98:99]
	global_load_dword v64, v[38:39], off nt
	s_add_u32 s98, s98, 0x4000
	s_addc_u32 s99, s99, 0
	v_lshl_add_u64 v[38:39], v[36:37], 0, s[98:99]
	global_load_dword v65, v[38:39], off nt
	s_add_u32 s98, s98, 0x4000
	s_addc_u32 s99, s99, 0
	v_lshl_add_u64 v[38:39], v[36:37], 0, s[98:99]
	global_load_dword v66, v[38:39], off nt
	s_add_u32 s98, s98, 0x4000
	s_addc_u32 s99, s99, 0
	v_lshl_add_u64 v[38:39], v[36:37], 0, s[98:99]
	global_load_dword v67, v[38:39], off nt
	s_add_u32 s98, s98, 0x4000
	s_addc_u32 s99, s99, 0
	v_lshl_add_u64 v[38:39], v[36:37], 0, s[98:99]
	global_load_dword v68, v[38:39], off nt
	s_add_u32 s98, s98, 0x4000
	s_addc_u32 s99, s99, 0
	v_lshl_add_u64 v[38:39], v[36:37], 0, s[98:99]
	global_load_dword v69, v[38:39], off nt
	s_add_u32 s98, s98, 0x4000
	s_addc_u32 s99, s99, 0
	v_lshl_add_u64 v[38:39], v[36:37], 0, s[98:99]
	global_load_dword v70, v[38:39], off nt
	s_add_u32 s98, s98, 0x4000
	s_addc_u32 s99, s99, 0
	v_lshl_add_u64 v[38:39], v[36:37], 0, s[98:99]
	global_load_dword v71, v[38:39], off nt
	s_add_u32 s98, s98, 0x4000
	s_addc_u32 s99, s99, 0
	v_lshl_add_u64 v[38:39], v[36:37], 0, s[98:99]
	global_load_dword v72, v[38:39], off nt
	s_add_u32 s98, s98, 0x4000
	s_addc_u32 s99, s99, 0
	v_lshl_add_u64 v[38:39], v[36:37], 0, s[98:99]
	global_load_dword v73, v[38:39], off nt
	s_add_u32 s98, s98, 0x4000
	s_addc_u32 s99, s99, 0
	v_lshl_add_u64 v[38:39], v[36:37], 0, s[98:99]
	global_load_dword v74, v[38:39], off nt
	s_add_u32 s98, s98, 0x4000
	s_addc_u32 s99, s99, 0
	v_lshl_add_u64 v[38:39], v[36:37], 0, s[98:99]
	global_load_dword v75, v[38:39], off nt
	s_add_u32 s98, s98, 0x4000
	s_addc_u32 s99, s99, 0
; template <int MAPID> __device__ __forceinline__ void transpose_item(const float* __restrict__ W, int K, int Nsrc, bf16_t* __restrict__ WT, int nblk, float* scr, int item, int lane) {
;     ...
;     for (int i = 0; i < 32; ++i) { const int kk = 2 * i + (lane >> 5); scr[kk * 33 + (lane & 31)] = srcc >= 0 ? __builtin_nontemporal_load(W + (size_t)(k0 + kk) * Nsrc + srcc) : 0.f; }
;     asm volatile("s_waitcnt lgkmcnt(0)" ::: "memory");
; __device__ __forceinline__ void tail_wout(const Args& a, unsigned char* lds, int rank, int count, int lane, int wave) {
;     ...
;     for (int it = rank * 8 + wave; it < 32 * 64; it += count * 8) transpose_item<0>(a.in[19], DM, DM, (bf16_t*)(a.ws + WS_WOUT), 64, scr, it, lane);
.Ltr_b_skip:
	s_waitcnt vmcnt(31)
	ds_write_b32 v13, v44
	s_waitcnt vmcnt(30)
	ds_write_b32 v13, v45 offset:264
	s_waitcnt vmcnt(29)
	ds_write_b32 v13, v46 offset:528
	s_waitcnt vmcnt(28)
	ds_write_b32 v13, v47 offset:792
	s_waitcnt vmcnt(27)
	ds_write_b32 v13, v48 offset:1056
	s_waitcnt vmcnt(26)
	ds_write_b32 v13, v49 offset:1320
	s_waitcnt vmcnt(25)
	ds_write_b32 v13, v50 offset:1584
	s_waitcnt vmcnt(24)
	ds_write_b32 v13, v51 offset:1848
	s_waitcnt vmcnt(23)
	ds_write_b32 v13, v52 offset:2112
	s_waitcnt vmcnt(22)
	ds_write_b32 v13, v53 offset:2376
	s_waitcnt vmcnt(21)
	ds_write_b32 v13, v54 offset:2640
	s_waitcnt vmcnt(20)
	ds_write_b32 v13, v55 offset:2904
	s_waitcnt vmcnt(19)
	ds_write_b32 v13, v56 offset:3168
	s_waitcnt vmcnt(18)
	ds_write_b32 v13, v57 offset:3432
	s_waitcnt vmcnt(17)
	ds_write_b32 v13, v58 offset:3696
	s_waitcnt vmcnt(16)
	ds_write_b32 v13, v59 offset:3960
	s_waitcnt vmcnt(15)
	ds_write_b32 v13, v60 offset:4224
	s_waitcnt vmcnt(14)
	ds_write_b32 v13, v61 offset:4488
	s_waitcnt vmcnt(13)
	ds_write_b32 v13, v62 offset:4752
	s_waitcnt vmcnt(12)
	ds_write_b32 v13, v63 offset:5016
	s_waitcnt vmcnt(11)
	ds_write_b32 v13, v64 offset:5280
	s_waitcnt vmcnt(10)
	ds_write_b32 v13, v65 offset:5544
	s_waitcnt vmcnt(9)
	ds_write_b32 v13, v66 offset:5808
	s_waitcnt vmcnt(8)
	ds_write_b32 v13, v67 offset:6072
	s_waitcnt vmcnt(7)
	ds_write_b32 v13, v68 offset:6336
	s_waitcnt vmcnt(6)
	ds_write_b32 v13, v69 offset:6600
	s_waitcnt vmcnt(5)
	ds_write_b32 v13, v70 offset:6864
	s_waitcnt vmcnt(4)
	ds_write_b32 v13, v71 offset:7128
	s_waitcnt vmcnt(3)
	ds_write_b32 v13, v72 offset:7392
	s_waitcnt vmcnt(2)
	ds_write_b32 v13, v73 offset:7656
	s_waitcnt vmcnt(1)
	ds_write_b32 v13, v74 offset:7920
	s_waitcnt vmcnt(0)
	ds_write_b32 v13, v75 offset:8184
	s_branch .LBB0_238

; template <int MAPID> __device__ __forceinline__ void transpose_item(const float* __restrict__ W, int K, int Nsrc, bf16_t* __restrict__ WT, int nblk, float* scr, int item, int lane) {
;     const int kb = item / nblk, nb = item % nblk, k0 = 64 * kb, n0 = 32 * nb;
;     const int srcc = colmap<MAPID>(n0 + (lane & 31));
; #pragma unroll 8
;     for (int i = 0; i < 32; ++i) { const int kk = 2 * i + (lane >> 5); scr[kk * 33 + (lane & 31)] = srcc >= 0 ? __builtin_nontemporal_load(W + (size_t)(k0 + kk) * Nsrc + srcc) : 0.f; }
;     asm volatile("s_waitcnt lgkmcnt(0)" ::: "memory");
; __device__ __forceinline__ void tail_wup_wdn(const Args& a, unsigned char* lds, int rank, int count, int lane, int wave) {
;     ...
;     for (int it = rank * 8 + wave; it < I_UP + I_DN; it += count * 8) {
;         if (it < I_UP) transpose_item<2>(a.in[20], DM, NUP, (bf16_t*)(a.ws + WS_WUP), NUP / 32, scr, it, lane);
;         else transpose_item<0>(a.in[23], DFF, DM, (bf16_t*)(a.ws + WS_WDN), 64, scr, it - I_UP, lane);
.LBB0_2046:
	s_cmpk_gt_i32 s9, 0x2bff
	s_mov_b64 s[2:3], -1
	s_cbranch_scc0 .LBB0_2050
	s_lshl_b32 s0, s11, 2
	s_and_b32 s0, s0, 0x1f80
	v_lshl_or_b32 v20, v22, 2, s0
	s_and_b32 s0, s13, 0xffc0
	v_or_b32_e32 v0, s0, v30
	v_lshl_or_b32 v0, v0, 13, v20
	v_lshl_add_u64 v[6:7], s[90:91], 0, v[0:1]
	v_or_b32_e32 v0, s0, v31
	v_lshl_or_b32 v0, v0, 13, v20
	v_lshl_add_u64 v[8:9], s[90:91], 0, v[0:1]
	v_or_b32_e32 v0, s0, v32
	v_lshl_or_b32 v0, v0, 13, v20
	v_lshl_add_u64 v[10:11], s[90:91], 0, v[0:1]
	v_or_b32_e32 v0, s0, v33
	v_lshl_or_b32 v0, v0, 13, v20
	v_lshl_add_u64 v[12:13], s[90:91], 0, v[0:1]
	v_or_b32_e32 v0, s0, v34
	v_lshl_or_b32 v0, v0, 13, v20
	v_lshl_add_u64 v[14:15], s[90:91], 0, v[0:1]
	v_or_b32_e32 v0, s0, v35
	v_lshl_or_b32 v0, v0, 13, v20
	v_lshl_add_u64 v[16:17], s[90:91], 0, v[0:1]
	v_or_b32_e32 v0, s0, v36
	v_lshl_or_b32 v0, v0, 13, v20
	v_lshl_add_u64 v[18:19], s[90:91], 0, v[0:1]
	v_or_b32_e32 v0, s0, v23
	v_lshl_or_b32 v0, v0, 13, v20
	v_lshl_add_u64 v[20:21], s[90:91], 0, v[0:1]
	s_mov_b64 s[2:3], 0
	v_mov_b32_e32 v0, v29
	v_mov_b32_e32 v62, 0
	v_mov_b32_e32 v63, 0
	v_mov_b32_e32 v64, 0
	v_mov_b32_e32 v65, 0
	v_mov_b32_e32 v66, 0
	v_mov_b32_e32 v67, 0
	v_mov_b32_e32 v68, 0
	v_mov_b32_e32 v69, 0
	v_mov_b32_e32 v70, 0
	v_mov_b32_e32 v71, 0
	v_mov_b32_e32 v72, 0
	v_mov_b32_e32 v73, 0
	v_mov_b32_e32 v74, 0
	v_mov_b32_e32 v75, 0
	v_mov_b32_e32 v76, 0
	v_mov_b32_e32 v77, 0
	v_mov_b32_e32 v78, 0
	v_mov_b32_e32 v79, 0
	v_mov_b32_e32 v80, 0
	v_mov_b32_e32 v81, 0
	v_mov_b32_e32 v82, 0
	v_mov_b32_e32 v83, 0
	v_mov_b32_e32 v84, 0
	v_mov_b32_e32 v85, 0
	v_mov_b32_e32 v86, 0
	v_mov_b32_e32 v87, 0
	v_mov_b32_e32 v88, 0
	v_mov_b32_e32 v89, 0
	v_mov_b32_e32 v90, 0
	v_mov_b32_e32 v91, 0
	v_mov_b32_e32 v92, 0
	v_mov_b32_e32 v93, 0
	v_lshl_add_u64 v[38:39], v[20:21], 0, s[2:3]
	global_load_dword v62, v[38:39], off nt
	v_lshl_add_u64 v[38:39], v[18:19], 0, s[2:3]
	global_load_dword v63, v[38:39], off nt
	v_lshl_add_u64 v[38:39], v[16:17], 0, s[2:3]
	global_load_dword v64, v[38:39], off nt
	v_lshl_add_u64 v[38:39], v[14:15], 0, s[2:3]
	global_load_dword v65, v[38:39], off nt
	v_lshl_add_u64 v[38:39], v[12:13], 0, s[2:3]
	global_load_dword v66, v[38:39], off nt
	v_lshl_add_u64 v[38:39], v[10:11], 0, s[2:3]
	global_load_dword v67, v[38:39], off nt
	v_lshl_add_u64 v[38:39], v[8:9], 0, s[2:3]
	global_load_dword v68, v[38:39], off nt
	v_lshl_add_u64 v[38:39], v[6:7], 0, s[2:3]
	global_load_dword v69, v[38:39], off nt
	s_add_u32 s2, s2, 0x20000
	s_addc_u32 s3, s3, 0
	v_lshl_add_u64 v[38:39], v[20:21], 0, s[2:3]
	global_load_dword v70, v[38:39], off nt
	v_lshl_add_u64 v[38:39], v[18:19], 0, s[2:3]
	global_load_dword v71, v[38:39], off nt
	v_lshl_add_u64 v[38:39], v[16:17], 0, s[2:3]
	global_load_dword v72, v[38:39], off nt
	v_lshl_add_u64 v[38:39], v[14:15], 0, s[2:3]
	global_load_dword v73, v[38:39], off nt
	v_lshl_add_u64 v[38:39], v[12:13], 0, s[2:3]
	global_load_dword v74, v[38:39], off nt
	v_lshl_add_u64 v[38:39], v[10:11], 0, s[2:3]
	global_load_dword v75, v[38:39], off nt
	v_lshl_add_u64 v[38:39], v[8:9], 0, s[2:3]
	global_load_dword v76, v[38:39], off nt
	v_lshl_add_u64 v[38:39], v[6:7], 0, s[2:3]
	global_load_dword v77, v[38:39], off nt
	s_add_u32 s2, s2, 0x20000
	s_addc_u32 s3, s3, 0
	v_lshl_add_u64 v[38:39], v[20:21], 0, s[2:3]
	global_load_dword v78, v[38:39], off nt
	v_lshl_add_u64 v[38:39], v[18:19], 0, s[2:3]
	global_load_dword v79, v[38:39], off nt
	v_lshl_add_u64 v[38:39], v[16:17], 0, s[2:3]
	global_load_dword v80, v[38:39], off nt
	v_lshl_add_u64 v[38:39], v[14:15], 0, s[2:3]
	global_load_dword v81, v[38:39], off nt
	v_lshl_add_u64 v[38:39], v[12:13], 0, s[2:3]
	global_load_dword v82, v[38:39], off nt
	v_lshl_add_u64 v[38:39], v[10:11], 0, s[2:3]
	global_load_dword v83, v[38:39], off nt
	v_lshl_add_u64 v[38:39], v[8:9], 0, s[2:3]
	global_load_dword v84, v[38:39], off nt
	v_lshl_add_u64 v[38:39], v[6:7], 0, s[2:3]
	global_load_dword v85, v[38:39], off nt
	s_add_u32 s2, s2, 0x20000
	s_addc_u32 s3, s3, 0
	v_lshl_add_u64 v[38:39], v[20:21], 0, s[2:3]
	global_load_dword v86, v[38:39], off nt
	v_lshl_add_u64 v[38:39], v[18:19], 0, s[2:3]
	global_load_dword v87, v[38:39], off nt
	v_lshl_add_u64 v[38:39], v[16:17], 0, s[2:3]
	global_load_dword v88, v[38:39], off nt
	v_lshl_add_u64 v[38:39], v[14:15], 0, s[2:3]
	global_load_dword v89, v[38:39], off nt
	v_lshl_add_u64 v[38:39], v[12:13], 0, s[2:3]
	global_load_dword v90, v[38:39], off nt
	v_lshl_add_u64 v[38:39], v[10:11], 0, s[2:3]
	global_load_dword v91, v[38:39], off nt
	v_lshl_add_u64 v[38:39], v[8:9], 0, s[2:3]
	global_load_dword v92, v[38:39], off nt
	v_lshl_add_u64 v[38:39], v[6:7], 0, s[2:3]
	global_load_dword v93, v[38:39], off nt
	s_add_u32 s2, s2, 0x20000
	s_addc_u32 s3, s3, 0
	s_waitcnt vmcnt(31)
	ds_write_b32 v0, v62
	s_waitcnt vmcnt(30)
	ds_write_b32 v0, v63 offset:264
	s_waitcnt vmcnt(29)
	ds_write_b32 v0, v64 offset:528
	s_waitcnt vmcnt(28)
	ds_write_b32 v0, v65 offset:792
	s_waitcnt vmcnt(27)
	ds_write_b32 v0, v66 offset:1056
	s_waitcnt vmcnt(26)
	ds_write_b32 v0, v67 offset:1320
	s_waitcnt vmcnt(25)
	ds_write_b32 v0, v68 offset:1584
	s_waitcnt vmcnt(24)
	ds_write_b32 v0, v69 offset:1848
	s_waitcnt vmcnt(23)
	ds_write_b32 v0, v70 offset:2112
	s_waitcnt vmcnt(22)
	ds_write_b32 v0, v71 offset:2376
	s_waitcnt vmcnt(21)
	ds_write_b32 v0, v72 offset:2640
	s_waitcnt vmcnt(20)
	ds_write_b32 v0, v73 offset:2904
	s_waitcnt vmcnt(19)
	ds_write_b32 v0, v74 offset:3168
	s_waitcnt vmcnt(18)
	ds_write_b32 v0, v75 offset:3432
	s_waitcnt vmcnt(17)
	ds_write_b32 v0, v76 offset:3696
	s_waitcnt vmcnt(16)
	ds_write_b32 v0, v77 offset:3960
	s_waitcnt vmcnt(15)
	ds_write_b32 v0, v78 offset:4224
	s_waitcnt vmcnt(14)
; __device__ __forceinline__ unsigned pk2(float lo, float hi) { const f32x2v v = {lo, hi}; const bf16x2v b = __builtin_convertvector(v, bf16x2v); return __builtin_bit_cast(unsigned, b); }
; template <int MAPID> __device__ __forceinline__ void transpose_item(const float* __restrict__ W, int K, int Nsrc, bf16_t* __restrict__ WT, int nblk, float* scr, int item, int lane) {
;     ...
;     for (int i = 0; i < 32; ++i) { const int kk = 2 * i + (lane >> 5); scr[kk * 33 + (lane & 31)] = srcc >= 0 ? __builtin_nontemporal_load(W + (size_t)(k0 + kk) * Nsrc + srcc) : 0.f; }
;     asm volatile("s_waitcnt lgkmcnt(0)" ::: "memory");
;     const int c = lane & 7;
; #pragma unroll
;     for (int j = 0; j < 4; ++j) { const int n = (lane >> 3) + 8 * j; const float* s = scr + (8 * c) * 33 + n;
;         u32x4 o; o.x = pk2(s[0 * 33], s[1 * 33]); o.y = pk2(s[2 * 33], s[3 * 33]); o.z = pk2(s[4 * 33], s[5 * 33]); o.w = pk2(s[6 * 33], s[7 * 33]);
;         *(u32x4*)(WT + (size_t)(n0 + n) * K + k0 + 8 * c) = o; }
;     asm volatile("s_waitcnt lgkmcnt(0)" ::: "memory");
	ds_write_b32 v0, v79 offset:4488
	s_waitcnt vmcnt(13)
	ds_write_b32 v0, v80 offset:4752
	s_waitcnt vmcnt(12)
	ds_write_b32 v0, v81 offset:5016
	s_waitcnt vmcnt(11)
	ds_write_b32 v0, v82 offset:5280
	s_waitcnt vmcnt(10)
	ds_write_b32 v0, v83 offset:5544
	s_waitcnt vmcnt(9)
	ds_write_b32 v0, v84 offset:5808
	s_waitcnt vmcnt(8)
	ds_write_b32 v0, v85 offset:6072
	s_waitcnt vmcnt(7)
	ds_write_b32 v0, v86 offset:6336
	s_waitcnt vmcnt(6)
	ds_write_b32 v0, v87 offset:6600
	s_waitcnt vmcnt(5)
	ds_write_b32 v0, v88 offset:6864
	s_waitcnt vmcnt(4)
	ds_write_b32 v0, v89 offset:7128
	s_waitcnt vmcnt(3)
	ds_write_b32 v0, v90 offset:7392
	s_waitcnt vmcnt(2)
	ds_write_b32 v0, v91 offset:7656
	s_waitcnt vmcnt(1)
	ds_write_b32 v0, v92 offset:7920
	s_waitcnt vmcnt(0)
	ds_write_b32 v0, v93 offset:8184
	s_lshl_b32 s2, s9, 5
	s_waitcnt lgkmcnt(0)
	s_add_i32 s0, s9, 0xd400
	s_and_b32 s2, s2, 0x7e0
	ds_read2_b32 v[10:11], v25 offset0:33 offset1:41
	ds_read2_b32 v[12:13], v25 offset1:8
	ds_read2_b32 v[14:15], v25 offset0:66 offset1:74
	ds_read2_b32 v[16:17], v25 offset0:99 offset1:107
	ds_read2_b32 v[18:19], v25 offset0:132 offset1:140
	ds_read2_b32 v[20:21], v25 offset0:165 offset1:173
	ds_read2_b32 v[38:39], v25 offset0:198 offset1:206
	ds_read2_b32 v[40:41], v25 offset0:231 offset1:239
	s_and_b32 s0, s0, 0xffc0
	v_or_b32_e32 v0, s2, v24
	s_lshl_b32 s0, s0, 1
	v_mul_u32_u24_e32 v0, 0x1600, v0
	v_lshl_add_u64 v[42:43], v[2:3], 0, s[0:1]
	v_lshlrev_b32_e32 v0, 1, v0
	v_lshl_add_u64 v[44:45], v[42:43], 0, v[0:1]
	v_or_b32_e32 v0, s2, v26
	s_waitcnt lgkmcnt(6)
	v_cvt_pk_bf16_f32 v6, v12, v10
	s_waitcnt lgkmcnt(4)
	v_cvt_pk_bf16_f32 v7, v14, v16
	s_waitcnt lgkmcnt(2)
	v_cvt_pk_bf16_f32 v8, v18, v20
	s_waitcnt lgkmcnt(0)
	v_cvt_pk_bf16_f32 v9, v38, v40
	v_mul_u32_u24_e32 v0, 0x1600, v0
	global_store_dwordx4 v[44:45], v[6:9], off
	v_lshlrev_b32_e32 v0, 1, v0
	s_nop 0
	v_cvt_pk_bf16_f32 v6, v13, v11
	v_cvt_pk_bf16_f32 v7, v15, v17
	v_cvt_pk_bf16_f32 v8, v19, v21
	v_cvt_pk_bf16_f32 v9, v39, v41
	v_lshl_add_u64 v[10:11], v[42:43], 0, v[0:1]
	ds_read2_b32 v[12:13], v25 offset0:16 offset1:24
	ds_read2_b32 v[14:15], v25 offset0:49 offset1:57
	ds_read2_b32 v[16:17], v25 offset0:82 offset1:90
	ds_read2_b32 v[18:19], v25 offset0:115 offset1:123
	ds_read2_b32 v[20:21], v25 offset0:148 offset1:156
	ds_read2_b32 v[38:39], v25 offset0:181 offset1:189
	ds_read2_b32 v[40:41], v25 offset0:214 offset1:222
	ds_read2_b32 v[44:45], v25 offset0:247 offset1:255
	v_or_b32_e32 v0, s2, v27
	v_mul_u32_u24_e32 v0, 0x1600, v0
	v_lshlrev_b32_e32 v0, 1, v0
	global_store_dwordx4 v[10:11], v[6:9], off
	v_lshl_add_u64 v[10:11], v[42:43], 0, v[0:1]
	v_or_b32_e32 v0, s2, v28
	v_mul_u32_u24_e32 v0, 0x1600, v0
	s_waitcnt lgkmcnt(6)
	v_cvt_pk_bf16_f32 v6, v12, v14
	s_waitcnt lgkmcnt(4)
	v_cvt_pk_bf16_f32 v7, v16, v18
	s_waitcnt lgkmcnt(2)
	v_cvt_pk_bf16_f32 v8, v20, v38
	s_waitcnt lgkmcnt(0)
	v_cvt_pk_bf16_f32 v9, v40, v44
	v_lshlrev_b32_e32 v0, 1, v0
	global_store_dwordx4 v[10:11], v[6:9], off
	v_lshl_add_u64 v[10:11], v[42:43], 0, v[0:1]
	s_mov_b64 s[2:3], 0
	v_cvt_pk_bf16_f32 v6, v13, v15
	v_cvt_pk_bf16_f32 v7, v17, v19
	v_cvt_pk_bf16_f32 v8, v21, v39
	v_cvt_pk_bf16_f32 v9, v41, v45
	global_store_dwordx4 v[10:11], v[6:9], off
	s_waitcnt lgkmcnt(0)
.LBB0_2050:
	s_and_b64 vcc, exec, s[2:3]
	s_cbranch_vccz .LBB0_2045
; template <int MAPID> __device__ __forceinline__ void transpose_item(const float* __restrict__ W, int K, int Nsrc, bf16_t* __restrict__ WT, int nblk, float* scr, int item, int lane) {
;     const int kb = item / nblk, nb = item % nblk, k0 = 64 * kb, n0 = 32 * nb;
;     const int srcc = colmap<MAPID>(n0 + (lane & 31));
; #pragma unroll 8
;     for (int i = 0; i < 32; ++i) { const int kk = 2 * i + (lane >> 5); scr[kk * 33 + (lane & 31)] = srcc >= 0 ? __builtin_nontemporal_load(W + (size_t)(k0 + kk) * Nsrc + srcc) : 0.f; }
; __device__ __forceinline__ void tail_wup_wdn(const Args& a, unsigned char* lds, int rank, int count, int lane, int wave) {
;     ...
;     for (int it = rank * 8 + wave; it < I_UP + I_DN; it += count * 8) {
;         if (it < I_UP) transpose_item<2>(a.in[20], DM, NUP, (bf16_t*)(a.ws + WS_WUP), NUP / 32, scr, it, lane);
;         else transpose_item<0>(a.in[23], DFF, DM, (bf16_t*)(a.ws + WS_WDN), 64, scr, it - I_UP, lane);
	s_mul_hi_i32 s0, s9, 0x2e8ba2e9
	s_lshr_b32 s2, s0, 31
	s_ashr_i32 s0, s0, 6
	s_add_i32 s0, s0, s2
	s_mul_i32 s2, s0, 0x160
	s_sub_i32 s3, s9, s2
	s_lshl_b32 s2, s0, 6
	s_lshl_b32 s0, s3, 5
	s_and_b32 s4, s0, 0xe0
	s_cmpk_lt_u32 s4, 0x80
	s_cselect_b64 vcc, -1, 0
	s_lshl_b32 s3, s3, 4
	v_or_b32_e32 v0, s4, v22
	s_and_b32 s3, s3, 0xffffff80
	v_or_b32_e32 v6, s3, v0
	s_addk_i32 s3, 0x1580
	v_add_u32_e32 v0, s3, v0
	v_cndmask_b32_e32 v0, v0, v6, vcc
	v_cmp_lt_i32_e32 vcc, -1, v0
	v_lshlrev_b64 v[20:21], 2, v[0:1]
	v_or_b32_e32 v0, s2, v31
	v_mad_i64_i32 v[8:9], s[4:5], v0, s14, v[20:21]
	v_or_b32_e32 v0, s2, v32
	v_mad_i64_i32 v[10:11], s[4:5], v0, s14, v[20:21]
	v_or_b32_e32 v0, s2, v33
	v_mad_i64_i32 v[12:13], s[4:5], v0, s14, v[20:21]
	v_or_b32_e32 v0, s2, v34
	v_mad_i64_i32 v[14:15], s[4:5], v0, s14, v[20:21]
	v_or_b32_e32 v0, s2, v35
	v_mad_i64_i32 v[16:17], s[4:5], v0, s14, v[20:21]
	v_or_b32_e32 v0, s2, v36
	v_or_b32_e32 v6, s2, v30
	v_mad_i64_i32 v[18:19], s[4:5], v0, s14, v[20:21]
	v_or_b32_e32 v0, s2, v23
	v_mad_i64_i32 v[6:7], s[4:5], v6, s14, v[20:21]
	v_mad_i64_i32 v[20:21], s[4:5], v0, s14, v[20:21]
	v_lshl_add_u64 v[6:7], s[84:85], 0, v[6:7]
	v_lshl_add_u64 v[8:9], s[84:85], 0, v[8:9]
	v_lshl_add_u64 v[10:11], s[84:85], 0, v[10:11]
	v_lshl_add_u64 v[12:13], s[84:85], 0, v[12:13]
	v_lshl_add_u64 v[14:15], s[84:85], 0, v[14:15]
	v_lshl_add_u64 v[16:17], s[84:85], 0, v[16:17]
	v_lshl_add_u64 v[18:19], s[84:85], 0, v[18:19]
	v_lshl_add_u64 v[20:21], s[84:85], 0, v[20:21]
	s_mov_b64 s[4:5], 0
	v_mov_b32_e32 v0, v29
	v_mov_b32_e32 v62, 0
	v_mov_b32_e32 v63, 0
	v_mov_b32_e32 v64, 0
	v_mov_b32_e32 v65, 0
	v_mov_b32_e32 v66, 0
	v_mov_b32_e32 v67, 0
	v_mov_b32_e32 v68, 0
	v_mov_b32_e32 v69, 0
	v_mov_b32_e32 v70, 0
	v_mov_b32_e32 v71, 0
	v_mov_b32_e32 v72, 0
	v_mov_b32_e32 v73, 0
	v_mov_b32_e32 v74, 0
	v_mov_b32_e32 v75, 0
	v_mov_b32_e32 v76, 0
	v_mov_b32_e32 v77, 0
	v_mov_b32_e32 v78, 0
	v_mov_b32_e32 v79, 0
	v_mov_b32_e32 v80, 0
	v_mov_b32_e32 v81, 0
	v_mov_b32_e32 v82, 0
	v_mov_b32_e32 v83, 0
	v_mov_b32_e32 v84, 0
	v_mov_b32_e32 v85, 0
	v_mov_b32_e32 v86, 0
	v_mov_b32_e32 v87, 0
	v_mov_b32_e32 v88, 0
	v_mov_b32_e32 v89, 0
	v_mov_b32_e32 v90, 0
	v_mov_b32_e32 v91, 0
	v_mov_b32_e32 v92, 0
	v_mov_b32_e32 v93, 0
	s_and_saveexec_b64 s[6:7], vcc
	v_lshl_add_u64 v[38:39], v[20:21], 0, s[4:5]
	global_load_dword v62, v[38:39], off nt
	v_lshl_add_u64 v[38:39], v[18:19], 0, s[4:5]
	global_load_dword v63, v[38:39], off nt
	v_lshl_add_u64 v[38:39], v[16:17], 0, s[4:5]
	global_load_dword v64, v[38:39], off nt
	v_lshl_add_u64 v[38:39], v[14:15], 0, s[4:5]
	global_load_dword v65, v[38:39], off nt
	v_lshl_add_u64 v[38:39], v[12:13], 0, s[4:5]
	global_load_dword v66, v[38:39], off nt
	v_lshl_add_u64 v[38:39], v[10:11], 0, s[4:5]
	global_load_dword v67, v[38:39], off nt
	v_lshl_add_u64 v[38:39], v[8:9], 0, s[4:5]
	global_load_dword v68, v[38:39], off nt
	v_lshl_add_u64 v[38:39], v[6:7], 0, s[4:5]
	global_load_dword v69, v[38:39], off nt
	s_add_u32 s4, s4, 0xb0000
	s_addc_u32 s5, s5, 0
	v_lshl_add_u64 v[38:39], v[20:21], 0, s[4:5]
	global_load_dword v70, v[38:39], off nt
	v_lshl_add_u64 v[38:39], v[18:19], 0, s[4:5]
	global_load_dword v71, v[38:39], off nt
	v_lshl_add_u64 v[38:39], v[16:17], 0, s[4:5]
	global_load_dword v72, v[38:39], off nt
	v_lshl_add_u64 v[38:39], v[14:15], 0, s[4:5]
	global_load_dword v73, v[38:39], off nt
	v_lshl_add_u64 v[38:39], v[12:13], 0, s[4:5]
	global_load_dword v74, v[38:39], off nt
	v_lshl_add_u64 v[38:39], v[10:11], 0, s[4:5]
	global_load_dword v75, v[38:39], off nt
	v_lshl_add_u64 v[38:39], v[8:9], 0, s[4:5]
	global_load_dword v76, v[38:39], off nt
	v_lshl_add_u64 v[38:39], v[6:7], 0, s[4:5]
	global_load_dword v77, v[38:39], off nt
	s_add_u32 s4, s4, 0xb0000
	s_addc_u32 s5, s5, 0
	v_lshl_add_u64 v[38:39], v[20:21], 0, s[4:5]
	global_load_dword v78, v[38:39], off nt
	v_lshl_add_u64 v[38:39], v[18:19], 0, s[4:5]
	global_load_dword v79, v[38:39], off nt
	v_lshl_add_u64 v[38:39], v[16:17], 0, s[4:5]
	global_load_dword v80, v[38:39], off nt
	v_lshl_add_u64 v[38:39], v[14:15], 0, s[4:5]
	global_load_dword v81, v[38:39], off nt
	v_lshl_add_u64 v[38:39], v[12:13], 0, s[4:5]
	global_load_dword v82, v[38:39], off nt
	v_lshl_add_u64 v[38:39], v[10:11], 0, s[4:5]
	global_load_dword v83, v[38:39], off nt
	v_lshl_add_u64 v[38:39], v[8:9], 0, s[4:5]
	global_load_dword v84, v[38:39], off nt
	v_lshl_add_u64 v[38:39], v[6:7], 0, s[4:5]
	global_load_dword v85, v[38:39], off nt
	s_add_u32 s4, s4, 0xb0000
	s_addc_u32 s5, s5, 0
	v_lshl_add_u64 v[38:39], v[20:21], 0, s[4:5]
	global_load_dword v86, v[38:39], off nt
	v_lshl_add_u64 v[38:39], v[18:19], 0, s[4:5]
	global_load_dword v87, v[38:39], off nt
	v_lshl_add_u64 v[38:39], v[16:17], 0, s[4:5]
	global_load_dword v88, v[38:39], off nt
	v_lshl_add_u64 v[38:39], v[14:15], 0, s[4:5]
	global_load_dword v89, v[38:39], off nt
	v_lshl_add_u64 v[38:39], v[12:13], 0, s[4:5]
	global_load_dword v90, v[38:39], off nt
	v_lshl_add_u64 v[38:39], v[10:11], 0, s[4:5]
	global_load_dword v91, v[38:39], off nt
	v_lshl_add_u64 v[38:39], v[8:9], 0, s[4:5]
	global_load_dword v92, v[38:39], off nt
	v_lshl_add_u64 v[38:39], v[6:7], 0, s[4:5]
	global_load_dword v93, v[38:39], off nt
	s_add_u32 s4, s4, 0xb0000
	s_addc_u32 s5, s5, 0
	s_or_b64 exec, exec, s[6:7]
	s_waitcnt vmcnt(31)
	ds_write_b32 v0, v62
	s_waitcnt vmcnt(30)
	ds_write_b32 v0, v63 offset:264
	s_waitcnt vmcnt(29)
	ds_write_b32 v0, v64 offset:528
	s_waitcnt vmcnt(28)
	ds_write_b32 v0, v65 offset:792
	s_waitcnt vmcnt(27)
	ds_write_b32 v0, v66 offset:1056
	s_waitcnt vmcnt(26)
	ds_write_b32 v0, v67 offset:1320
	s_waitcnt vmcnt(25)
	ds_write_b32 v0, v68 offset:1584
	s_waitcnt vmcnt(24)
	ds_write_b32 v0, v69 offset:1848
	s_waitcnt vmcnt(23)
	ds_write_b32 v0, v70 offset:2112
	s_waitcnt vmcnt(22)
	ds_write_b32 v0, v71 offset:2376
	s_waitcnt vmcnt(21)
	ds_write_b32 v0, v72 offset:2640
	s_waitcnt vmcnt(20)
	ds_write_b32 v0, v73 offset:2904
	s_waitcnt vmcnt(19)
	ds_write_b32 v0, v74 offset:3168
	s_waitcnt vmcnt(18)
	ds_write_b32 v0, v75 offset:3432
	s_waitcnt vmcnt(17)
	ds_write_b32 v0, v76 offset:3696
	s_waitcnt vmcnt(16)
	ds_write_b32 v0, v77 offset:3960
	s_waitcnt vmcnt(15)
	ds_write_b32 v0, v78 offset:4224
	s_waitcnt vmcnt(14)
	ds_write_b32 v0, v79 offset:4488
	s_waitcnt vmcnt(13)
	ds_write_b32 v0, v80 offset:4752
	s_waitcnt vmcnt(12)
	ds_write_b32 v0, v81 offset:5016
	s_waitcnt vmcnt(11)
	ds_write_b32 v0, v82 offset:5280
	s_waitcnt vmcnt(10)
	ds_write_b32 v0, v83 offset:5544
	s_waitcnt vmcnt(9)
	ds_write_b32 v0, v84 offset:5808
	s_waitcnt vmcnt(8)
	ds_write_b32 v0, v85 offset:6072
	s_waitcnt vmcnt(7)
	ds_write_b32 v0, v86 offset:6336
	s_waitcnt vmcnt(6)
	ds_write_b32 v0, v87 offset:6600
	s_waitcnt vmcnt(5)
	ds_write_b32 v0, v88 offset:6864
	s_waitcnt vmcnt(4)
	ds_write_b32 v0, v89 offset:7128
	s_waitcnt vmcnt(3)
	ds_write_b32 v0, v90 offset:7392
	s_waitcnt vmcnt(2)
	ds_write_b32 v0, v91 offset:7656
	s_waitcnt vmcnt(1)
	ds_write_b32 v0, v92 offset:7920
	s_waitcnt vmcnt(0)
	ds_write_b32 v0, v93 offset:8184
	s_branch .LBB0_2044
